# code placement: GEMM k-loop shifted 36 bytes and attention loop shifted 36 bytes by unreachable pad nops
# baseline (speedup 1.0000x reference)
; __device__ __forceinline__ size_t a_base(const GDesc& d, const Unit& u, size_t tstepA) { return (size_t)u.pm * tstepA + (d.amode == 1 ? (size_t)u.pn * 512 : (size_t)0); }
; #define PG8_STAGE(bufoff, gbase, voff) do { _Pragma("unroll") for (int _i = 0; _i < 2; ++_i) \
;         __builtin_amdgcn_global_load_lds((const unsigned*)((const char*)(gbase) + (voff)[_i]), (LAS unsigned*)(lds + (bufoff) + ldsw + _i * 8192), 16, 0, 0); } while (0)
; #define PG8_LDA(dst, b, h) do { _Pragma("unroll") for (int m = 0; m < 4; ++m) _Pragma("unroll") for (int k = 0; k < 2; ++k) dst[m][k] = *(const LAS bf16x8*)(lds + PG8_SA(b, h) + aoff + m * 2048 + k * 1024); } while (0)
; #define PG8_LDB(dst, b, h) do { _Pragma("unroll") for (int n = 0; n < 2; ++n) _Pragma("unroll") for (int k = 0; k < 2; ++k) dst[n][k] = *(const LAS bf16x8*)(lds + PG8_SB(b, h) + boff + n * 2048 + k * 1024); } while (0)
; #define PG8_WAIT_V(n) asm volatile("s_waitcnt vmcnt(" #n ")" ::: "memory")
; #define PG8_WAIT_L(n) asm volatile("s_waitcnt lgkmcnt(" #n ")" ::: "memory")
; #define PG8_BAR __builtin_amdgcn_s_barrier()
; #define PG8_SCHED __builtin_amdgcn_sched_barrier(0)
; __device__ __forceinline__ void gemm_generic(LAS unsigned char* lds, const GDesc& d, int G, int bx) {
;     ...
;         const bool has_next = S.next(ui + 1, nxt);
;         const char* nA = has_next ? d.A + a_base(d, nxt, tstepA) : cA; const char* nB = has_next ? d.Bt + (size_t)nxt.pn * tstepB : cB;
;         for (int t = 0; t < nt; t += 2) {
;             const bool last = (t == nt - 2);
;             const char* a1 = cA + a_koff(d, t + 1);
;             const char* a2 = last ? nA : cA + a_koff(d, t + 2); const char* b2 = last ? nB : cB + (size_t)(t + 2) * kstep;
;             const char* a3 = last ? nA + a_koff(d, 1) : cA + a_koff(d, t + 3); const char* b3 = b2 + kstep;
;             PG8_LDB(B0, 0, 0); PG8_LDB(B1, 0, 1); PG8_SCHED; PG8_LDA(At, 0, 0); PG8_STAGE(PG8_SA(1, 1), a1 + hstepA, voffA);
;             PG8_WAIT_V(8); PG8_WAIT_L(0); PG8_BAR; PG8_MMA(0, 0, At, B0); PG8_MMA(0, 1, At, B1); PG8_BAR; PG8_SCHED;
;             PG8_LDA(At, 0, 1); PG8_STAGE(PG8_SB(0, 0), b2, voffB); PG8_STAGE(PG8_SB(0, 1), b2 + hstepB, voffB); PG8_STAGE(PG8_SA(0, 0), a2, voffA);
;             PG8_WAIT_V(8); PG8_WAIT_L(0); PG8_BAR; PG8_MMA(1, 0, At, B0); PG8_MMA(1, 1, At, B1); PG8_BAR; PG8_SCHED;
.LBB0_253:
	s_and_b64 s[44:45], exec, s[44:45]
	s_cselect_b32 s45, s83, s16
	s_cselect_b32 s44, s82, s15
	s_nop 0
	s_nop 0
	s_nop 0
	s_nop 0
	s_nop 0
	s_nop 0
	s_nop 0
	s_nop 0
	s_nop 0
	ds_read_b128 v[130:133], v250
	ds_read_b128 v[134:137], v250 offset:1024
	ds_read_b128 v[138:141], v250 offset:2048
	ds_read_b128 v[142:145], v250 offset:3072
	ds_read_b128 v[146:149], v251
	ds_read_b128 v[150:153], v251 offset:1024
	ds_read_b128 v[154:157], v251 offset:2048
	ds_read_b128 v[158:161], v251 offset:3072
	s_add_u32 s34, s12, s34
	s_addc_u32 s35, s13, s35
	s_add_i32 m0, s97, 0xc000
	ds_read_b128 v[162:165], v232
	ds_read_b128 v[166:169], v232 offset:1024
	ds_read_b128 v[170:173], v232 offset:2048
	ds_read_b128 v[174:177], v232 offset:3072
	ds_read_b128 v[178:181], v232 offset:4096
	ds_read_b128 v[182:185], v232 offset:5120
	ds_read_b128 v[186:189], v232 offset:6144
	ds_read_b128 v[190:193], v232 offset:7168
	global_load_lds_dwordx4 v198, s[34:35]
	s_add_i32 m0, s97, 0xe000
	s_nop 0
	global_load_lds_dwordx4 v202, s[34:35]
	s_waitcnt vmcnt(8)
	s_waitcnt lgkmcnt(0)
	s_barrier
	s_setprio 1
	s_waitcnt lgkmcnt(0)
	v_mfma_f32_16x16x32_bf16 v[124:127], v[130:133], v[162:165], 0
	v_mfma_f32_16x16x32_bf16 v[120:123], v[138:141], v[162:165], 0
	v_mfma_f32_16x16x32_bf16 v[112:115], v[130:133], v[170:173], 0
	v_mfma_f32_16x16x32_bf16 v[104:107], v[138:141], v[170:173], 0
	v_mfma_f32_16x16x32_bf16 v[96:99], v[130:133], v[178:181], 0
	v_mfma_f32_16x16x32_bf16 v[88:91], v[138:141], v[178:181], 0
	v_mfma_f32_16x16x32_bf16 v[80:83], v[130:133], v[186:189], 0
	v_mfma_f32_16x16x32_bf16 v[72:75], v[138:141], v[186:189], 0
	v_mfma_f32_16x16x32_bf16 v[124:127], v[134:137], v[166:169], v[124:127]
	v_mfma_f32_16x16x32_bf16 v[120:123], v[142:145], v[166:169], v[120:123]
	v_mfma_f32_16x16x32_bf16 v[112:115], v[134:137], v[174:177], v[112:115]
	v_mfma_f32_16x16x32_bf16 v[104:107], v[142:145], v[174:177], v[104:107]
	v_mfma_f32_16x16x32_bf16 v[96:99], v[134:137], v[182:185], v[96:99]
	v_mfma_f32_16x16x32_bf16 v[88:91], v[142:145], v[182:185], v[88:91]
	v_mfma_f32_16x16x32_bf16 v[80:83], v[134:137], v[190:193], v[80:83]
	v_mfma_f32_16x16x32_bf16 v[72:75], v[142:145], v[190:193], v[72:75]
	s_setprio 0
	s_setprio 1
	v_mfma_f32_16x16x32_bf16 v[116:119], v[146:149], v[162:165], 0
	v_mfma_f32_16x16x32_bf16 v[108:111], v[154:157], v[162:165], 0
	v_mfma_f32_16x16x32_bf16 v[100:103], v[146:149], v[170:173], 0
	v_mfma_f32_16x16x32_bf16 v[92:95], v[154:157], v[170:173], 0
	v_mfma_f32_16x16x32_bf16 v[84:87], v[146:149], v[178:181], 0
	v_mfma_f32_16x16x32_bf16 v[76:79], v[154:157], v[178:181], 0
	v_mfma_f32_16x16x32_bf16 v[68:71], v[146:149], v[186:189], 0
	v_mfma_f32_16x16x32_bf16 v[64:67], v[154:157], v[186:189], 0
	v_mfma_f32_16x16x32_bf16 v[116:119], v[150:153], v[166:169], v[116:119]
	v_mfma_f32_16x16x32_bf16 v[108:111], v[158:161], v[166:169], v[108:111]
	v_mfma_f32_16x16x32_bf16 v[100:103], v[150:153], v[174:177], v[100:103]
	v_mfma_f32_16x16x32_bf16 v[92:95], v[158:161], v[174:177], v[92:95]
	v_mfma_f32_16x16x32_bf16 v[84:87], v[150:153], v[182:185], v[84:87]
	v_mfma_f32_16x16x32_bf16 v[76:79], v[158:161], v[182:185], v[76:79]
	v_mfma_f32_16x16x32_bf16 v[68:71], v[150:153], v[190:193], v[68:71]
	v_mfma_f32_16x16x32_bf16 v[64:67], v[158:161], v[190:193], v[64:67]
	s_setprio 0
	s_barrier
	s_add_i32 m0, s95, 0x10000
	ds_read_b128 v[162:165], v232 offset:16384
	ds_read_b128 v[166:169], v232 offset:17408
	ds_read_b128 v[170:173], v232 offset:18432
	ds_read_b128 v[174:177], v232 offset:19456
	ds_read_b128 v[178:181], v232 offset:20480
	ds_read_b128 v[182:185], v232 offset:21504
	ds_read_b128 v[186:189], v232 offset:22528
	ds_read_b128 v[190:193], v232 offset:23552
	global_load_lds_dwordx4 v200, s[44:45]
	s_add_i32 m0, s95, 0x12000
	s_add_u32 s34, s44, s76
	s_addc_u32 s35, s45, s77
	global_load_lds_dwordx4 v204, s[44:45]
	s_add_i32 m0, s95, 0x14000
	s_nop 0
	global_load_lds_dwordx4 v200, s[34:35]
	s_add_i32 m0, s95, 0x16000
	s_nop 0
	global_load_lds_dwordx4 v204, s[34:35]
	s_mov_b32 m0, s97
	s_nop 0
	global_load_lds_dwordx4 v198, s[28:29]
	s_mov_b32 m0, s27
	s_nop 0
	global_load_lds_dwordx4 v202, s[28:29]
	s_waitcnt vmcnt(8)
	s_waitcnt lgkmcnt(0)
	s_barrier
	s_setprio 1
	s_waitcnt lgkmcnt(0)
	v_mfma_f32_16x16x32_bf16 v[60:63], v[130:133], v[162:165], 0
	v_mfma_f32_16x16x32_bf16 v[56:59], v[138:141], v[162:165], 0
	v_mfma_f32_16x16x32_bf16 v[48:51], v[130:133], v[170:173], 0
	v_mfma_f32_16x16x32_bf16 v[40:43], v[138:141], v[170:173], 0
	v_mfma_f32_16x16x32_bf16 v[32:35], v[130:133], v[178:181], 0
	v_mfma_f32_16x16x32_bf16 v[24:27], v[138:141], v[178:181], 0
	v_mfma_f32_16x16x32_bf16 v[16:19], v[130:133], v[186:189], 0
	v_mfma_f32_16x16x32_bf16 v[8:11], v[138:141], v[186:189], 0
	v_mfma_f32_16x16x32_bf16 v[60:63], v[134:137], v[166:169], v[60:63]
	v_mfma_f32_16x16x32_bf16 v[56:59], v[142:145], v[166:169], v[56:59]
	v_mfma_f32_16x16x32_bf16 v[48:51], v[134:137], v[174:177], v[48:51]
	v_mfma_f32_16x16x32_bf16 v[40:43], v[142:145], v[174:177], v[40:43]
	v_mfma_f32_16x16x32_bf16 v[32:35], v[134:137], v[182:185], v[32:35]
	v_mfma_f32_16x16x32_bf16 v[24:27], v[142:145], v[182:185], v[24:27]
	v_mfma_f32_16x16x32_bf16 v[16:19], v[134:137], v[190:193], v[16:19]
	v_mfma_f32_16x16x32_bf16 v[8:11], v[142:145], v[190:193], v[8:11]
	s_setprio 0
	s_setprio 1
	v_mfma_f32_16x16x32_bf16 v[52:55], v[146:149], v[162:165], 0
	v_mfma_f32_16x16x32_bf16 v[44:47], v[154:157], v[162:165], 0
	v_mfma_f32_16x16x32_bf16 v[36:39], v[146:149], v[170:173], 0
	v_mfma_f32_16x16x32_bf16 v[28:31], v[154:157], v[170:173], 0
	v_mfma_f32_16x16x32_bf16 v[20:23], v[146:149], v[178:181], 0
	v_mfma_f32_16x16x32_bf16 v[12:15], v[154:157], v[178:181], 0
	v_mfma_f32_16x16x32_bf16 v[4:7], v[146:149], v[186:189], 0
	v_mfma_f32_16x16x32_bf16 v[0:3], v[154:157], v[186:189], 0
	v_mfma_f32_16x16x32_bf16 v[52:55], v[150:153], v[166:169], v[52:55]
	v_mfma_f32_16x16x32_bf16 v[44:47], v[158:161], v[166:169], v[44:47]
	v_mfma_f32_16x16x32_bf16 v[36:39], v[150:153], v[174:177], v[36:39]
	v_mfma_f32_16x16x32_bf16 v[28:31], v[158:161], v[174:177], v[28:31]
	v_mfma_f32_16x16x32_bf16 v[20:23], v[150:153], v[182:185], v[20:23]
	v_mfma_f32_16x16x32_bf16 v[12:15], v[158:161], v[182:185], v[12:15]
	v_mfma_f32_16x16x32_bf16 v[4:7], v[150:153], v[190:193], v[4:7]
	v_mfma_f32_16x16x32_bf16 v[0:3], v[158:161], v[190:193], v[0:3]
	s_setprio 0
	s_barrier
; #define PG8_STAGE(bufoff, gbase, voff) do { _Pragma("unroll") for (int _i = 0; _i < 2; ++_i) \
;         __builtin_amdgcn_global_load_lds((const unsigned*)((const char*)(gbase) + (voff)[_i]), (LAS unsigned*)(lds + (bufoff) + ldsw + _i * 8192), 16, 0, 0); } while (0)
; #define PG8_LDA(dst, b, h) do { _Pragma("unroll") for (int m = 0; m < 4; ++m) _Pragma("unroll") for (int k = 0; k < 2; ++k) dst[m][k] = *(const LAS bf16x8*)(lds + PG8_SA(b, h) + aoff + m * 2048 + k * 1024); } while (0)
; #define PG8_LDB(dst, b, h) do { _Pragma("unroll") for (int n = 0; n < 2; ++n) _Pragma("unroll") for (int k = 0; k < 2; ++k) dst[n][k] = *(const LAS bf16x8*)(lds + PG8_SB(b, h) + boff + n * 2048 + k * 1024); } while (0)
; #define PG8_MMA(ai, bj, At, Bt) do { __builtin_amdgcn_s_setprio(1); _Pragma("unroll") for (int m = 0; m < 4; ++m) _Pragma("unroll") for (int n = 0; n < 2; ++n) _Pragma("unroll") for (int k = 0; k < 2; ++k) \
;         acc[ai][bj][m][n] = __builtin_amdgcn_mfma_f32_16x16x32_bf16(Bt[n][k], At[m][k], acc[ai][bj][m][n], 0, 0, 0); __builtin_amdgcn_s_setprio(0); } while (0)
; #define PG8_WAIT_V(n) asm volatile("s_waitcnt vmcnt(" #n ")" ::: "memory")
; #define PG8_WAIT_L(n) asm volatile("s_waitcnt lgkmcnt(" #n ")" ::: "memory")
; #define PG8_BAR __builtin_amdgcn_s_barrier()
; #define PG8_SCHED __builtin_amdgcn_sched_barrier(0)
; __device__ __forceinline__ void gemm_generic(LAS unsigned char* lds, const GDesc& d, int G, int bx) {
;     ...
;         for (int t = 0; t < nt; t += 2) {
;             const bool last = (t == nt - 2);
;             const char* a1 = cA + a_koff(d, t + 1);
;             const char* a2 = last ? nA : cA + a_koff(d, t + 2); const char* b2 = last ? nB : cB + (size_t)(t + 2) * kstep;
;             const char* a3 = last ? nA + a_koff(d, 1) : cA + a_koff(d, t + 3); const char* b3 = b2 + kstep;
;     ...
;             PG8_LDB(B0, 1, 0); PG8_LDB(B1, 1, 1); PG8_SCHED; PG8_LDA(At, 1, 0); PG8_STAGE(PG8_SA(0, 1), a2 + hstepA, voffA);
;             PG8_WAIT_V(8); PG8_WAIT_L(0); PG8_BAR; PG8_MMA(0, 0, At, B0); PG8_MMA(0, 1, At, B1); PG8_BAR; PG8_SCHED;
;             PG8_LDA(At, 1, 1); PG8_STAGE(PG8_SB(1, 0), b3, voffB); PG8_STAGE(PG8_SB(1, 1), b3 + hstepB, voffB); PG8_STAGE(PG8_SA(1, 0), a3, voffA);
;             PG8_WAIT_V(8); PG8_WAIT_L(0); PG8_BAR; PG8_MMA(1, 0, At, B0); PG8_MMA(1, 1, At, B1); PG8_BAR; PG8_SCHED;
	s_add_i32 s26, 0, 0x1c000
	ds_read_b128 v[130:133], v252
	ds_read_b128 v[134:137], v252 offset:1024
	ds_read_b128 v[138:141], v252 offset:2048
	ds_read_b128 v[142:145], v252 offset:3072
	ds_read_b128 v[146:149], v253
	ds_read_b128 v[150:153], v253 offset:1024
	ds_read_b128 v[154:157], v253 offset:2048
	ds_read_b128 v[158:161], v253 offset:3072
	s_add_u32 s28, s28, s74
	s_addc_u32 s29, s29, s75
	s_mov_b32 m0, s64
	ds_read_b128 v[162:165], v232 offset:32768
	ds_read_b128 v[166:169], v232 offset:33792
	ds_read_b128 v[170:173], v232 offset:34816
	ds_read_b128 v[174:177], v232 offset:35840
	ds_read_b128 v[178:181], v232 offset:36864
	ds_read_b128 v[182:185], v232 offset:37888
	ds_read_b128 v[186:189], v232 offset:38912
	ds_read_b128 v[190:193], v232 offset:39936
	global_load_lds_dwordx4 v198, s[28:29]
	s_mov_b32 m0, s65
	s_nop 0
	global_load_lds_dwordx4 v202, s[28:29]
	s_waitcnt vmcnt(8)
	s_waitcnt lgkmcnt(0)
	s_barrier
	s_setprio 1
	s_waitcnt lgkmcnt(0)
	v_mfma_f32_16x16x32_bf16 v[124:127], v[130:133], v[162:165], v[124:127]
	v_mfma_f32_16x16x32_bf16 v[120:123], v[138:141], v[162:165], v[120:123]
	v_mfma_f32_16x16x32_bf16 v[112:115], v[130:133], v[170:173], v[112:115]
	v_mfma_f32_16x16x32_bf16 v[104:107], v[138:141], v[170:173], v[104:107]
	v_mfma_f32_16x16x32_bf16 v[96:99], v[130:133], v[178:181], v[96:99]
	v_mfma_f32_16x16x32_bf16 v[88:91], v[138:141], v[178:181], v[88:91]
	v_mfma_f32_16x16x32_bf16 v[80:83], v[130:133], v[186:189], v[80:83]
	v_mfma_f32_16x16x32_bf16 v[72:75], v[138:141], v[186:189], v[72:75]
	v_mfma_f32_16x16x32_bf16 v[124:127], v[134:137], v[166:169], v[124:127]
	v_mfma_f32_16x16x32_bf16 v[120:123], v[142:145], v[166:169], v[120:123]
	v_mfma_f32_16x16x32_bf16 v[112:115], v[134:137], v[174:177], v[112:115]
	v_mfma_f32_16x16x32_bf16 v[104:107], v[142:145], v[174:177], v[104:107]
	v_mfma_f32_16x16x32_bf16 v[96:99], v[134:137], v[182:185], v[96:99]
	v_mfma_f32_16x16x32_bf16 v[88:91], v[142:145], v[182:185], v[88:91]
	v_mfma_f32_16x16x32_bf16 v[80:83], v[134:137], v[190:193], v[80:83]
	v_mfma_f32_16x16x32_bf16 v[72:75], v[142:145], v[190:193], v[72:75]
	s_setprio 0
	s_setprio 1
	v_mfma_f32_16x16x32_bf16 v[116:119], v[146:149], v[162:165], v[116:119]
	v_mfma_f32_16x16x32_bf16 v[108:111], v[154:157], v[162:165], v[108:111]
	v_mfma_f32_16x16x32_bf16 v[100:103], v[146:149], v[170:173], v[100:103]
	v_mfma_f32_16x16x32_bf16 v[92:95], v[154:157], v[170:173], v[92:95]
	v_mfma_f32_16x16x32_bf16 v[84:87], v[146:149], v[178:181], v[84:87]
	v_mfma_f32_16x16x32_bf16 v[76:79], v[154:157], v[178:181], v[76:79]
	v_mfma_f32_16x16x32_bf16 v[68:71], v[146:149], v[186:189], v[68:71]
	v_mfma_f32_16x16x32_bf16 v[64:67], v[154:157], v[186:189], v[64:67]
	v_mfma_f32_16x16x32_bf16 v[116:119], v[150:153], v[166:169], v[116:119]
	v_mfma_f32_16x16x32_bf16 v[108:111], v[158:161], v[166:169], v[108:111]
	v_mfma_f32_16x16x32_bf16 v[100:103], v[150:153], v[174:177], v[100:103]
	v_mfma_f32_16x16x32_bf16 v[92:95], v[158:161], v[174:177], v[92:95]
	v_mfma_f32_16x16x32_bf16 v[84:87], v[150:153], v[182:185], v[84:87]
	v_mfma_f32_16x16x32_bf16 v[76:79], v[158:161], v[182:185], v[76:79]
	v_mfma_f32_16x16x32_bf16 v[68:71], v[150:153], v[190:193], v[68:71]
	v_mfma_f32_16x16x32_bf16 v[64:67], v[158:161], v[190:193], v[64:67]
	s_setprio 0
	s_barrier
	s_add_u32 s46, s44, s20
	s_addc_u32 s47, s45, s21
	s_add_i32 m0, s95, 0x18000
	ds_read_b128 v[162:165], v232 offset:49152
	ds_read_b128 v[166:169], v232 offset:50176
	ds_read_b128 v[170:173], v232 offset:51200
	ds_read_b128 v[174:177], v232 offset:52224
	ds_read_b128 v[178:181], v232 offset:53248
	ds_read_b128 v[182:185], v232 offset:54272
	ds_read_b128 v[186:189], v232 offset:55296
	ds_read_b128 v[190:193], v232 offset:56320
	global_load_lds_dwordx4 v200, s[46:47]
	s_add_i32 m0, s95, 0x1a000
	s_nop 0
	global_load_lds_dwordx4 v204, s[46:47]
	s_add_u32 s46, s34, s20
	s_addc_u32 s47, s35, s21
	s_add_i32 m0, s95, 0x1c000
	s_nop 0
	global_load_lds_dwordx4 v200, s[46:47]
	s_add_i32 m0, s95, 0x1e000
	s_nop 0
	global_load_lds_dwordx4 v204, s[46:47]
	s_mov_b32 m0, s30
	s_nop 0
	global_load_lds_dwordx4 v198, s[24:25]
	s_mov_b32 m0, s31
	s_nop 0
	global_load_lds_dwordx4 v202, s[24:25]
	s_add_u32 s10, s10, 0x180
	s_addc_u32 s11, s11, 0
	s_add_u32 s15, s15, 0x100
	s_addc_u32 s16, s16, 0
	s_mov_b32 s17, s22
	s_cmp_ge_u32 s22, s87
	s_cbranch_scc1 .Lg_ctl_done_p
	s_or_b32 s22, s17, 1
	s_lshl_b64 s[34:35], s[22:23], 7
	s_add_i32 s22, s17, 2
	s_lshl_b64 s[28:29], s[22:23], 7
	s_add_i32 s24, s17, 3
	s_mov_b32 s25, s23
	s_lshl_b64 s[24:25], s[24:25], 7
	s_and_b64 vcc, exec, s[84:85]
	s_cbranch_scc1 .Lg_ctl_std_p
	s_add_u32 s34, s10, 0xfffffe80
	s_addc_u32 s35, s11, -1
	s_add_u32 s28, s10, 0xffffff80
	s_addc_u32 s29, s11, -1
	s_mov_b64 s[24:25], s[10:11]

; #define PG8_MMA(ai, bj, At, Bt) do { __builtin_amdgcn_s_setprio(1); _Pragma("unroll") for (int m = 0; m < 4; ++m) _Pragma("unroll") for (int n = 0; n < 2; ++n) _Pragma("unroll") for (int k = 0; k < 2; ++k) \
;         acc[ai][bj][m][n] = __builtin_amdgcn_mfma_f32_16x16x32_bf16(Bt[n][k], At[m][k], acc[ai][bj][m][n], 0, 0, 0); __builtin_amdgcn_s_setprio(0); } while (0)
; #define PG8_WAIT_V(n) asm volatile("s_waitcnt vmcnt(" #n ")" ::: "memory")
; #define PG8_WAIT_L(n) asm volatile("s_waitcnt lgkmcnt(" #n ")" ::: "memory")
; #define PG8_BAR __builtin_amdgcn_s_barrier()
; #define PG8_SCHED __builtin_amdgcn_sched_barrier(0)
; __device__ __forceinline__ void gemm_generic(LAS unsigned char* lds, const GDesc& d, int G, int bx) {
;     ...
;             PG8_WAIT_V(8); PG8_WAIT_L(0); PG8_BAR; PG8_MMA(1, 0, At, B0); PG8_MMA(1, 1, At, B1); PG8_BAR; PG8_SCHED;
;         }
;         if (wr == 0) PG8_BAR;
;         run_epi(d, acc, cur, wr, wc, fr, fq);
;         if (!has_next) break;
.Lg_ctl_done:
	s_waitcnt vmcnt(8)
	s_waitcnt lgkmcnt(0)
	s_barrier
	s_setprio 1
	s_waitcnt lgkmcnt(0)
	v_mfma_f32_16x16x32_bf16 v[60:63], v[130:133], v[162:165], v[60:63]
	v_mfma_f32_16x16x32_bf16 v[56:59], v[138:141], v[162:165], v[56:59]
	v_mfma_f32_16x16x32_bf16 v[48:51], v[130:133], v[170:173], v[48:51]
	v_mfma_f32_16x16x32_bf16 v[40:43], v[138:141], v[170:173], v[40:43]
	v_mfma_f32_16x16x32_bf16 v[32:35], v[130:133], v[178:181], v[32:35]
	v_mfma_f32_16x16x32_bf16 v[24:27], v[138:141], v[178:181], v[24:27]
	v_mfma_f32_16x16x32_bf16 v[16:19], v[130:133], v[186:189], v[16:19]
	v_mfma_f32_16x16x32_bf16 v[8:11], v[138:141], v[186:189], v[8:11]
	v_mfma_f32_16x16x32_bf16 v[60:63], v[134:137], v[166:169], v[60:63]
	v_mfma_f32_16x16x32_bf16 v[56:59], v[142:145], v[166:169], v[56:59]
	v_mfma_f32_16x16x32_bf16 v[48:51], v[134:137], v[174:177], v[48:51]
	v_mfma_f32_16x16x32_bf16 v[40:43], v[142:145], v[174:177], v[40:43]
	v_mfma_f32_16x16x32_bf16 v[32:35], v[134:137], v[182:185], v[32:35]
	v_mfma_f32_16x16x32_bf16 v[24:27], v[142:145], v[182:185], v[24:27]
	v_mfma_f32_16x16x32_bf16 v[16:19], v[134:137], v[190:193], v[16:19]
	v_mfma_f32_16x16x32_bf16 v[8:11], v[142:145], v[190:193], v[8:11]
	s_setprio 0
	s_setprio 1
	v_mfma_f32_16x16x32_bf16 v[52:55], v[146:149], v[162:165], v[52:55]
	v_mfma_f32_16x16x32_bf16 v[44:47], v[154:157], v[162:165], v[44:47]
	v_mfma_f32_16x16x32_bf16 v[36:39], v[146:149], v[170:173], v[36:39]
	v_mfma_f32_16x16x32_bf16 v[28:31], v[154:157], v[170:173], v[28:31]
	v_mfma_f32_16x16x32_bf16 v[20:23], v[146:149], v[178:181], v[20:23]
	v_mfma_f32_16x16x32_bf16 v[12:15], v[154:157], v[178:181], v[12:15]
	v_mfma_f32_16x16x32_bf16 v[4:7], v[146:149], v[186:189], v[4:7]
	v_mfma_f32_16x16x32_bf16 v[0:3], v[154:157], v[186:189], v[0:3]
	v_mfma_f32_16x16x32_bf16 v[52:55], v[150:153], v[166:169], v[52:55]
	v_mfma_f32_16x16x32_bf16 v[44:47], v[158:161], v[166:169], v[44:47]
	v_mfma_f32_16x16x32_bf16 v[36:39], v[150:153], v[174:177], v[36:39]
	v_mfma_f32_16x16x32_bf16 v[28:31], v[158:161], v[174:177], v[28:31]
	v_mfma_f32_16x16x32_bf16 v[20:23], v[150:153], v[182:185], v[20:23]
	v_mfma_f32_16x16x32_bf16 v[12:15], v[158:161], v[182:185], v[12:15]
	v_mfma_f32_16x16x32_bf16 v[4:7], v[150:153], v[190:193], v[4:7]
	v_mfma_f32_16x16x32_bf16 v[0:3], v[158:161], v[190:193], v[0:3]
	s_setprio 0
	s_barrier
	s_cmp_ge_u32 s17, s87
	s_cbranch_scc0 .Lg_body
	s_branch .LBB0_267
	s_nop 0
	s_nop 0
	s_nop 0
	s_nop 0
	s_nop 0
	s_nop 0
	s_nop 0

; #define SBAR() __builtin_amdgcn_sched_barrier(0)
; __device__ __forceinline__ int v_st(int k, int c) { const int kk = (k & ~0xC) | ((k & 4) << 1) | ((k & 8) >> 1); return ((kk >> 3) * 4 + (c >> 5)) * 512 + ((kk & 7) * 32 + (c & 31)) * 2; }
; __device__ __forceinline__ int v_rd_base(int lane) { return ((lane & 3) << 3) | (((lane >> 2) & 3) << 6) | (((lane >> 4) & 1) << 5) | (((lane >> 5) & 1) << 8); }
; #define VMW() asm volatile("s_waitcnt vmcnt(0)" ::: "memory")
; #define SLOAD(R_, k0) do { const size_t tr_ = (size_t)tokrow((R_).b, (k0) + srow); const bf16_t* kp_ = (const bf16_t*)(T.ws + OFF_KF) + tr_ * 3072 + (R_).h * 192 + c0 * 8; const bf16_t* vp_ = (const bf16_t*)(T.ws + OFF_V) + tr_ * 2048 + (R_).h * 128 + c0 * 8; \
;         S.st_v0 = ld8(vp_); S.st_v1 = ld8(vp_ + 64); S.st_k0 = ld8(kp_); S.st_k1 = ld8(kp_ + 64); S.st_k2 = ld8(kp_ + 128); } while (0)
; __device__ __forceinline__ void partialSM(f32x16& p0, f32x16& p1, float& m_reg, float& mn, float& alpha) {
;     ...
;     if (__builtin_expect(__all((pmax - m_reg) * SCALE <= THR), 1)) { mn = m_reg; alpha = 1.f; }
;     else { mn = fmaxf(m_reg, pmax); alpha = __builtin_amdgcn_exp2f((m_reg - mn) * C2); m_reg = mn; }
;     const float mnL = -mn * C2;
; #pragma unroll
;     for (int r = 0; r < 16; ++r) p0[r] = fmaf(p0[r], C2, mnL);
; #pragma unroll
;     for (int r = 0; r < 16; ++r) p1[r] = fmaf(p1[r], C2, mnL);
; #pragma unroll
;     for (int r = 0; r < 16; ++r) p0[r] = __builtin_amdgcn_exp2f(p0[r]);
; __device__ __forceinline__ void attn_block(const Ref& cur, const Ref& nxt, const Tens& T, char* lds, Seam& S, bool nostore) {
;     ...
;     float m_reg = -1e30f, l_reg = 0; f32x16 o[4] = {};
;     const int srow = tid >> 3, c0 = tid & 7, vst0 = v_st(srow, c0 * 8), kws = KSWZ(srow, c0 * 16);
;     const int vb0 = (int)(uintptr_t)V_lds + v_rd_base(lane);
;     ...
;     f32x16 pA0, pA1, pB0, pB1; float mnA, mnB, alA, alB; bf16x8 pa0, pa1, pa2, pa3;
;     char* qbase = lds + LDS_QR + wid * QR_WAVE + r32 * QR_ROW + hi * 16;
; #pragma unroll
;     for (int j = 0; j < 8; ++j) *(bf16x8*)(qbase + j * 32) = S.qr[4 + j];
;     SBAR();
;     SWRITE_HV(0); SBAR();
;     if (NT > 1) { SLOAD(cur, KBASE(1)); }
;     SBAR(); qkt<0>(pA0, pA1, K_lds, r32, hi, S.qr, qbase);
;     MASKT(pA0, pA1, 0); partialSM(pA0, pA1, m_reg, mnA, alA);
;     if (NT > 1) { VMW(); SWRITE_H(1); }
;     __syncthreads();
.LBB0_1477:
	v_max_f32_e32 v35, 0xf149f2ca, v32
	v_cndmask_b32_e64 v208, v35, v229, s[0:1]
	v_mul_f32_e32 v32, 0xbdd53b94, v208
	v_fmamk_f32 v16, v16, 0x3dd53b94, v32
	v_exp_f32_e32 v233, v16
	v_sub_f32_e32 v16, 0xf149f2ca, v35
	v_mul_f32_e32 v16, 0x3dd53b94, v16
	v_exp_f32_e32 v16, v16
	v_fmamk_f32 v17, v17, 0x3dd53b94, v32
	v_fmamk_f32 v18, v18, 0x3dd53b94, v32
	v_fmamk_f32 v19, v19, 0x3dd53b94, v32
	v_cndmask_b32_e64 v203, v16, 1.0, s[0:1]
	s_and_b32 s0, s14, 0x3fffffc0
	s_lshl_b32 s0, s0, 2
	v_fmamk_f32 v20, v20, 0x3dd53b94, v32
	v_fmamk_f32 v21, v21, 0x3dd53b94, v32
	v_fmamk_f32 v22, v22, 0x3dd53b94, v32
	v_fmamk_f32 v23, v23, 0x3dd53b94, v32
	v_fmamk_f32 v24, v24, 0x3dd53b94, v32
	v_fmamk_f32 v25, v25, 0x3dd53b94, v32
	v_fmamk_f32 v26, v26, 0x3dd53b94, v32
	v_fmamk_f32 v27, v27, 0x3dd53b94, v32
	v_fmamk_f32 v28, v28, 0x3dd53b94, v32
	v_fmamk_f32 v29, v29, 0x3dd53b94, v32
	v_fmamk_f32 v30, v30, 0x3dd53b94, v32
	v_fmamk_f32 v31, v31, 0x3dd53b94, v32
	v_pk_fma_f32 v[180:181], v[0:1], s[18:19], v[32:33] op_sel_hi:[1,0,0]
	s_add_i32 s0, s0, 0
	v_lshlrev_b32_e32 v1, 4, v189
	v_exp_f32_e32 v235, v17
	v_exp_f32_e32 v231, v18
	v_exp_f32_e32 v234, v19
	v_exp_f32_e32 v223, v20
	v_exp_f32_e32 v232, v21
	v_exp_f32_e32 v221, v22
	v_exp_f32_e32 v222, v23
	v_exp_f32_e32 v217, v24
	v_exp_f32_e32 v220, v25
	v_exp_f32_e32 v215, v26
	v_exp_f32_e32 v218, v27
	v_exp_f32_e32 v213, v28
	v_exp_f32_e32 v219, v29
	v_exp_f32_e32 v214, v30
	v_exp_f32_e32 v216, v31
	v_pk_fma_f32 v[178:179], v[2:3], s[18:19], v[32:33] op_sel_hi:[1,0,0]
	s_add_i32 s0, s0, 0x14800
	v_lshlrev_b32_e32 v0, 3, v189
	v_and_b32_e32 v1, 0xc0, v1
	v_lshlrev_b32_e32 v2, 1, v189
	v_and_or_b32 v1, v0, 24, v1
	v_and_b32_e32 v2, 32, v2
	v_and_b32_e32 v0, 0x100, v0
	s_cmp_lg_u32 0, -1
	v_or3_b32 v0, v1, v2, v0
	s_cselect_b32 s1, 0, 0
	v_pk_fma_f32 v[166:167], v[14:15], s[18:19], v[32:33] op_sel_hi:[1,0,0]
	v_pk_fma_f32 v[168:169], v[12:13], s[18:19], v[32:33] op_sel_hi:[1,0,0]
	v_pk_fma_f32 v[170:171], v[10:11], s[18:19], v[32:33] op_sel_hi:[1,0,0]
	v_pk_fma_f32 v[172:173], v[8:9], s[18:19], v[32:33] op_sel_hi:[1,0,0]
	v_pk_fma_f32 v[174:175], v[6:7], s[18:19], v[32:33] op_sel_hi:[1,0,0]
	v_pk_fma_f32 v[176:177], v[4:5], s[18:19], v[32:33] op_sel_hi:[1,0,0]
	v_add_u32_e32 v199, s1, v0
	s_mov_b32 s31, 0
	s_cmp_lt_u32 s35, 3
	v_add_u32_e32 v206, 0xe400, v202
	v_cmp_gt_u32_e64 s[40:41], 32, v189
	v_lshlrev_b32_e32 v196, 1, v33
	v_lshl_add_u32 v198, v190, 2, s0
	v_lshl_add_u32 v193, v34, 2, s0
	s_waitcnt lgkmcnt(0)
	s_barrier
	s_cbranch_scc1 .LBB0_1496
	s_lshl_b32 s14, s13, 12
	s_mov_b32 s25, s23
	s_add_i32 s14, s14, -16
	s_lshl_b64 s[0:1], s[24:25], 1
	v_readlane_b32 s4, v246, 23
	v_readlane_b32 s5, v246, 24
	s_add_u32 s0, s4, s0
	s_addc_u32 s1, s5, s1
	s_lshl_b32 s22, s28, 7
	v_lshl_add_u64 v[184:185], s[0:1], 0, v[196:197]
	s_lshl_b64 s[0:1], s[22:23], 1
	v_readlane_b32 s4, v246, 25
	v_readlane_b32 s5, v246, 26
	s_add_u32 s0, s4, s0
	s_addc_u32 s1, s5, s1
	v_lshl_add_u64 v[186:187], s[0:1], 0, v[196:197]
	s_add_i32 s0, s30, 0xffffff80
	v_add_u32_e32 v0, s0, v190
	v_mov_b32_e32 v205, 0
	s_mov_b32 s26, 2
	v_sub_u32_e32 v209, v0, v34
	v_mov_b32_e32 v48, 0
	v_mov_b32_e32 v49, v205
	v_mov_b32_e32 v50, v205
	v_mov_b32_e32 v51, v205
	v_mov_b32_e32 v52, v205
	v_mov_b32_e32 v53, v205
	v_mov_b32_e32 v54, v205
	v_mov_b32_e32 v55, v205
	v_mov_b32_e32 v56, v205
	v_mov_b32_e32 v57, v205
	v_mov_b32_e32 v58, v205
	v_mov_b32_e32 v59, v205
	v_mov_b32_e32 v60, v205
	v_mov_b32_e32 v61, v205
	v_mov_b32_e32 v62, v205
	v_mov_b32_e32 v63, v205
	v_mov_b32_e32 v32, 0
	v_mov_b32_e32 v33, v205
	v_mov_b32_e32 v34, v205
	v_mov_b32_e32 v35, v205
	v_mov_b32_e32 v36, v205
	v_mov_b32_e32 v37, v205
	v_mov_b32_e32 v38, v205
	v_mov_b32_e32 v39, v205
	v_mov_b32_e32 v40, v205
	v_mov_b32_e32 v41, v205
	v_mov_b32_e32 v42, v205
	v_mov_b32_e32 v43, v205
	v_mov_b32_e32 v44, v205
	v_mov_b32_e32 v45, v205
	v_mov_b32_e32 v46, v205
	v_mov_b32_e32 v47, v205
	v_mov_b32_e32 v16, 0
	v_mov_b32_e32 v17, v205
	v_mov_b32_e32 v18, v205
	v_mov_b32_e32 v19, v205
	v_mov_b32_e32 v20, v205
	v_mov_b32_e32 v21, v205
	v_mov_b32_e32 v22, v205
	v_mov_b32_e32 v23, v205
	v_mov_b32_e32 v24, v205
	v_mov_b32_e32 v25, v205
	v_mov_b32_e32 v26, v205
	v_mov_b32_e32 v27, v205
	v_mov_b32_e32 v28, v205
	v_mov_b32_e32 v29, v205
	v_mov_b32_e32 v30, v205
	v_mov_b32_e32 v31, v205
	v_mov_b32_e32 v0, 0
	v_mov_b32_e32 v1, v205
	v_mov_b32_e32 v2, v205
	v_mov_b32_e32 v3, v205
	v_mov_b32_e32 v4, v205
	v_mov_b32_e32 v5, v205
	v_mov_b32_e32 v6, v205
	v_mov_b32_e32 v7, v205
	v_mov_b32_e32 v8, v205
	v_mov_b32_e32 v9, v205
	v_mov_b32_e32 v10, v205
	v_mov_b32_e32 v11, v205
	v_mov_b32_e32 v12, v205
	v_mov_b32_e32 v13, v205
	v_mov_b32_e32 v14, v205
	v_mov_b32_e32 v15, v205
	s_branch .LBB0_1481
	s_nop 0
	s_nop 0
	s_nop 0
	s_nop 0
	s_nop 0
	s_nop 0
	s_nop 0
	s_nop 0
	s_nop 0

; __device__ __forceinline__ void partialSM(f32x16& p0, f32x16& p1, float& m_reg, float& mn, float& alpha) {
;     ...
;     if (__builtin_expect(__all((pmax - m_reg) * SCALE <= THR), 1)) { mn = m_reg; alpha = 1.f; }
;     else { mn = fmaxf(m_reg, pmax); alpha = __builtin_amdgcn_exp2f((m_reg - mn) * C2); m_reg = mn; }
.LBB0_1493:
	s_waitcnt vmcnt(0)
	v_max_f32_e32 v146, v208, v208
	v_max_f32_e32 v147, v146, v166
	v_sub_f32_e32 v146, v208, v147
	v_mul_f32_e32 v146, 0x3dd53b94, v146
	v_exp_f32_e32 v146, v146
	s_nop 0
	v_cndmask_b32_e64 v146, v146, 1.0, s[42:43]
	v_cmp_gt_f32_e32 vcc, 1.0, v146
	s_cbranch_vccz .LBB0_1480
	s_and_saveexec_b64 s[0:1], s[40:41]
	s_cbranch_execz .LBB0_1479
	ds_write_b32 v198, v146 offset:128
	s_branch .LBB0_1479
	s_nop 0
	s_nop 0
	s_nop 0
	s_nop 0
	s_nop 0
	s_nop 0
	s_nop 0
